# chain step: all slot operands requested up front, MFMA chain without LDS waits; LoRA / g2 slice staging loads de-serialised
# speedup vs baseline: 1.0066x; 1.0066x over previous
; #define LAS __attribute__((address_space(3)))
; __device__ __forceinline__ unsigned f2bf(float f) { unsigned u = __builtin_bit_cast(unsigned, f); return (u + 0x7fffu + ((u >> 16) & 1u)) >> 16; }
; __device__ void phase_rwkv_dist(const Params& p, LAS unsigned char* lds, int wg, int nwg) {
;     ...
;         {   LAS bf16_t* w2h = (LAS bf16_t*)(lds + RC_W2H); LAS bf16_t* a2h = (LAS bf16_t*)(lds + RC_A2H);
;             for (int i = tid; i < 96 * 64; i += 512) { const int k = i >> 6, ch = i & 63;
;                 w2h[ch * 104 + k] = (bf16_t)f2bf(p.in[I_W2][(size_t)k * D_RWKV + h * 64 + ch]); a2h[ch * 104 + k] = (bf16_t)f2bf(p.in[I_A2][(size_t)k * D_RWKV + h * 64 + ch]); } }
.LBB0_641:
	v_ashrrev_i32_e32 v28, 6, v2
	v_ashrrev_i32_e32 v29, 31, v28
	v_lshlrev_b64 v[30:31], 13, v[28:29]
	v_lshl_or_b32 v30, v0, 2, v30
	s_mov_b64 s[98:99], s[86:87]
	s_mov_b64 s[100:101], s[90:91]
	global_load_dword v100, v30, s[98:99]
	global_load_dword v112, v30, s[100:101]
	s_add_u32 s98, s98, 0x10000
	s_addc_u32 s99, s99, 0
	s_add_u32 s100, s100, 0x10000
	s_addc_u32 s101, s101, 0
	global_load_dword v101, v30, s[98:99]
	global_load_dword v113, v30, s[100:101]
	s_add_u32 s98, s98, 0x10000
	s_addc_u32 s99, s99, 0
	s_add_u32 s100, s100, 0x10000
	s_addc_u32 s101, s101, 0
	global_load_dword v102, v30, s[98:99]
	global_load_dword v114, v30, s[100:101]
	s_add_u32 s98, s98, 0x10000
	s_addc_u32 s99, s99, 0
	s_add_u32 s100, s100, 0x10000
	s_addc_u32 s101, s101, 0
	global_load_dword v103, v30, s[98:99]
	global_load_dword v115, v30, s[100:101]
	s_add_u32 s98, s98, 0x10000
	s_addc_u32 s99, s99, 0
	s_add_u32 s100, s100, 0x10000
	s_addc_u32 s101, s101, 0
	global_load_dword v104, v30, s[98:99]
	global_load_dword v116, v30, s[100:101]
	s_add_u32 s98, s98, 0x10000
	s_addc_u32 s99, s99, 0
	s_add_u32 s100, s100, 0x10000
	s_addc_u32 s101, s101, 0
	global_load_dword v105, v30, s[98:99]
	global_load_dword v117, v30, s[100:101]
	s_add_u32 s98, s98, 0x10000
	s_addc_u32 s99, s99, 0
	s_add_u32 s100, s100, 0x10000
	s_addc_u32 s101, s101, 0
	global_load_dword v106, v30, s[98:99]
	global_load_dword v118, v30, s[100:101]
	s_add_u32 s98, s98, 0x10000
	s_addc_u32 s99, s99, 0
	s_add_u32 s100, s100, 0x10000
	s_addc_u32 s101, s101, 0
	global_load_dword v107, v30, s[98:99]
	global_load_dword v119, v30, s[100:101]
	s_add_u32 s98, s98, 0x10000
	s_addc_u32 s99, s99, 0
	s_add_u32 s100, s100, 0x10000
	s_addc_u32 s101, s101, 0
	global_load_dword v108, v30, s[98:99]
	global_load_dword v120, v30, s[100:101]
	s_add_u32 s98, s98, 0x10000
	s_addc_u32 s99, s99, 0
	s_add_u32 s100, s100, 0x10000
	s_addc_u32 s101, s101, 0
	global_load_dword v109, v30, s[98:99]
	global_load_dword v121, v30, s[100:101]
	s_add_u32 s98, s98, 0x10000
	s_addc_u32 s99, s99, 0
	s_add_u32 s100, s100, 0x10000
	s_addc_u32 s101, s101, 0
	global_load_dword v110, v30, s[98:99]
	global_load_dword v122, v30, s[100:101]
	s_add_u32 s98, s98, 0x10000
	s_addc_u32 s99, s99, 0
	s_add_u32 s100, s100, 0x10000
	s_addc_u32 s101, s101, 0
	global_load_dword v111, v30, s[98:99]
	global_load_dword v123, v30, s[100:101]
	v_add_u32_e32 v28, v28, v204
	v_lshl_add_u32 v32, v28, 1, 0
	v_add_u32_e32 v28, 0x20400, v32
	v_add_u32_e32 v33, 0x23800, v32
	s_waitcnt vmcnt(23)
	v_bfe_u32 v29, v100, 16, 1
	v_add3_u32 v100, v100, v29, s21
	ds_write_b16_d16_hi v28, v100
	s_waitcnt vmcnt(22)
	v_bfe_u32 v29, v112, 16, 1
	v_add3_u32 v112, v112, v29, s21
	ds_write_b16_d16_hi v33, v112
	s_waitcnt vmcnt(21)
	v_bfe_u32 v29, v101, 16, 1
	v_add3_u32 v101, v101, v29, s21
	ds_write_b16_d16_hi v28, v101 offset:16
	s_waitcnt vmcnt(20)
	v_bfe_u32 v29, v113, 16, 1
	v_add3_u32 v113, v113, v29, s21
	ds_write_b16_d16_hi v33, v113 offset:16
	s_waitcnt vmcnt(19)
	v_bfe_u32 v29, v102, 16, 1
	v_add3_u32 v102, v102, v29, s21
	ds_write_b16_d16_hi v28, v102 offset:32
	s_waitcnt vmcnt(18)
	v_bfe_u32 v29, v114, 16, 1
	v_add3_u32 v114, v114, v29, s21
	ds_write_b16_d16_hi v33, v114 offset:32
	s_waitcnt vmcnt(17)
	v_bfe_u32 v29, v103, 16, 1
	v_add3_u32 v103, v103, v29, s21
	ds_write_b16_d16_hi v28, v103 offset:48
	s_waitcnt vmcnt(16)
	v_bfe_u32 v29, v115, 16, 1
	v_add3_u32 v115, v115, v29, s21
	ds_write_b16_d16_hi v33, v115 offset:48
	s_waitcnt vmcnt(15)
	v_bfe_u32 v29, v104, 16, 1
	v_add3_u32 v104, v104, v29, s21
	ds_write_b16_d16_hi v28, v104 offset:64
	s_waitcnt vmcnt(14)
	v_bfe_u32 v29, v116, 16, 1
	v_add3_u32 v116, v116, v29, s21
	ds_write_b16_d16_hi v33, v116 offset:64
	s_waitcnt vmcnt(13)
	v_bfe_u32 v29, v105, 16, 1
	v_add3_u32 v105, v105, v29, s21
	ds_write_b16_d16_hi v28, v105 offset:80
	s_waitcnt vmcnt(12)
	v_bfe_u32 v29, v117, 16, 1
	v_add3_u32 v117, v117, v29, s21
	ds_write_b16_d16_hi v33, v117 offset:80
	s_waitcnt vmcnt(11)
	v_bfe_u32 v29, v106, 16, 1
	v_add3_u32 v106, v106, v29, s21
	ds_write_b16_d16_hi v28, v106 offset:96
	s_waitcnt vmcnt(10)
	v_bfe_u32 v29, v118, 16, 1
	v_add3_u32 v118, v118, v29, s21
	ds_write_b16_d16_hi v33, v118 offset:96
	s_waitcnt vmcnt(9)
	v_bfe_u32 v29, v107, 16, 1
	v_add3_u32 v107, v107, v29, s21
	ds_write_b16_d16_hi v28, v107 offset:112
	s_waitcnt vmcnt(8)
	v_bfe_u32 v29, v119, 16, 1
	v_add3_u32 v119, v119, v29, s21
	ds_write_b16_d16_hi v33, v119 offset:112
	s_waitcnt vmcnt(7)
	v_bfe_u32 v29, v108, 16, 1
	v_add3_u32 v108, v108, v29, s21
	ds_write_b16_d16_hi v28, v108 offset:128
	s_waitcnt vmcnt(6)
	v_bfe_u32 v29, v120, 16, 1
	v_add3_u32 v120, v120, v29, s21
	ds_write_b16_d16_hi v33, v120 offset:128
	s_waitcnt vmcnt(5)
	v_bfe_u32 v29, v109, 16, 1
	v_add3_u32 v109, v109, v29, s21
	ds_write_b16_d16_hi v28, v109 offset:144
	s_waitcnt vmcnt(4)
	v_bfe_u32 v29, v121, 16, 1
	v_add3_u32 v121, v121, v29, s21
	ds_write_b16_d16_hi v33, v121 offset:144
	s_waitcnt vmcnt(3)
	v_bfe_u32 v29, v110, 16, 1
	v_add3_u32 v110, v110, v29, s21
	ds_write_b16_d16_hi v28, v110 offset:160
	s_waitcnt vmcnt(2)
	v_bfe_u32 v29, v122, 16, 1
	v_add3_u32 v122, v122, v29, s21
	ds_write_b16_d16_hi v33, v122 offset:160
	s_waitcnt vmcnt(1)
	v_bfe_u32 v29, v111, 16, 1
	v_add3_u32 v111, v111, v29, s21
	ds_write_b16_d16_hi v28, v111 offset:176
	s_waitcnt vmcnt(0)
	v_bfe_u32 v29, v123, 16, 1
	v_add3_u32 v123, v123, v29, s21
	ds_write_b16_d16_hi v33, v123 offset:176

; #define LAS __attribute__((address_space(3)))
; #define MFMA16(a, b, c) __builtin_amdgcn_mfma_f32_16x16x16bf16_1k(a, b, c, 0, 0, 0)
; __device__ void phase_rwkv_dist(const Params& p, LAS unsigned char* lds, int wg, int nwg) {
;     ...
;                 LAS const unsigned char* sl = lds + (ci % RD_NL) * RC_SL;
;                 const bf16x8 at0 = *(LAS const bf16x8*)(sl + RC_AT + lane * 16), at1 = *(LAS const bf16x8*)(sl + RC_AT + 1024 + lane * 16);
;                 const bf16x8 rt0 = *(LAS const bf16x8*)(sl + RC_RT + lane * 16), rt1 = *(LAS const bf16x8*)(sl + RC_RT + 1024 + lane * 16);
;                 const bf16x8 mm0 = *(LAS const bf16x8*)(sl + RD_MM + lane * 32), mm1 = *(LAS const bf16x8*)(sl + RD_MM + lane * 32 + 16);
;                 const bf16x4 vt = *(LAS const bf16x4*)(sl + RC_VT + lane * 8);
;                 bf16x8 bk[4]; f32x4 gl[4];
; #pragma unroll
;                 for (int ct = 0; ct < 4; ++ct) { bk[ct] = *(LAS const bf16x8*)(sl + RD_BK + (ct * 64 + lane) * 16); gl[ct] = *(LAS const f32x4*)(sl + RC_GL + (16 * ct + 4 * q) * 4); }
;                 asm volatile("s_waitcnt lgkmcnt(0)" ::: "memory");
;                 lflag[12] = (unsigned)(ci + 1);
;                 const bf16x4 mak = __builtin_shufflevector(mm0, mm0, 0, 1, 2, 3), mrb = __builtin_shufflevector(mm0, mm0, 4, 5, 6, 7), mrk = __builtin_shufflevector(mm1, mm1, 0, 1, 2, 3), ti = __builtin_shufflevector(mm1, mm1, 4, 5, 6, 7);
;                 const bf16x8 sop0 = pk8(Sacc[0], Sacc[1]), sop1 = pk8(Sacc[2], Sacc[3]);
;                 f32x4 X = MFMA32(at0, sop0, zero4); X = MFMA32(at1, sop1, X); X = MFMA16(mak, vt, X);
;                 const f32x4 U = MFMA16(ti, pk4(X), zero4);
;                 const bf16x4 up = pk4(U);
;                 f32x4 Y = MFMA32(rt0, sop0, zero4); Y = MFMA32(rt1, sop1, Y); Y = MFMA16(mrb, up, Y); Y = MFMA16(mrk, vt, Y);
; #pragma unroll
;                 for (int ct = 0; ct < 4; ++ct) { const bf16x4 btc = __builtin_shufflevector(bk[ct], bk[ct], 0, 1, 2, 3), ktc = __builtin_shufflevector(bk[ct], bk[ct], 4, 5, 6, 7);
;                     Sacc[ct] = MFMA16(btc, up, Sacc[ct]); Sacc[ct] = MFMA16(ktc, vt, Sacc[ct]); Sacc[ct] = Sacc[ct] * gl[ct]; }
;                 const f32x4 Yt = MFMA16(pk4(Y), ident, zero4);
;                 *(u32x2*)(YRAW + ((size_t)bh * SEQ + 16 * ci + r) * 64 + 16 * qw + 4 * q) = __builtin_bit_cast(u32x2, pk4(Yt));
.LBB0_778:
	s_mulk_i32 s16, 0x2b00
	s_add_i32 s2, s16, 0
	v_add_u32_e32 v0, s2, v196
	v_add_u32_e32 v90, s2, v198
	v_add_u32_e32 v82, s2, v203
	v_add_u32_e32 v98, s2, v189
	ds_read_b128 v[104:107], v0
	ds_read_b128 v[108:111], v0 offset:1024
	ds_read_b128 v[112:115], v90 offset:8192
	ds_read_b64 v[102:103], v82 offset:10240
	ds_read_b128 v[120:123], v90 offset:8208
	ds_read_b128 v[116:119], v0 offset:2048
	ds_read_b128 v[128:131], v0 offset:3072
	ds_read_b128 v[132:135], v0 offset:4096
	ds_read_b128 v[136:139], v0 offset:5120
	ds_read_b128 v[140:143], v0 offset:6144
	ds_read_b128 v[144:147], v0 offset:7168
	ds_read_b128 v[124:127], v98 offset:10752
	ds_read_b128 v[160:163], v98 offset:10816
	ds_read_b128 v[168:171], v98 offset:10880
	ds_read_b128 v[176:179], v98 offset:10944
	v_cvt_pk_bf16_f32 v82, v56, v57
	v_cvt_pk_bf16_f32 v83, v58, v59
	v_cvt_pk_bf16_f32 v84, v64, v65
	v_cvt_pk_bf16_f32 v85, v66, v67
	v_cvt_pk_bf16_f32 v86, v60, v61
	v_cvt_pk_bf16_f32 v87, v62, v63
	v_cvt_pk_bf16_f32 v88, v52, v53
	v_cvt_pk_bf16_f32 v89, v54, v55
	s_lshl_b32 s72, s6, 4
	s_cmpk_eq_i32 s7, 0x200
	s_mov_b32 s6, s7
	s_waitcnt lgkmcnt(14)
	v_mfma_f32_16x16x32_bf16 v[70:73], v[104:107], v[82:85], 0
	s_waitcnt lgkmcnt(13)
	v_mfma_f32_16x16x32_bf16 v[70:73], v[108:111], v[86:89], v[70:73]
	s_waitcnt lgkmcnt(11)
	s_nop 7
	v_mfma_f32_16x16x16_bf16 v[70:73], v[112:113], v[102:103], v[70:73]
	s_waitcnt lgkmcnt(9)
	v_mfma_f32_16x16x32_bf16 v[180:183], v[116:119], v[82:85], 0
	s_waitcnt lgkmcnt(8)
	v_mfma_f32_16x16x32_bf16 v[180:183], v[128:131], v[86:89], v[180:183]
	s_nop 3
	v_cvt_pk_bf16_f32 v70, v70, v71
	v_cvt_pk_bf16_f32 v71, v72, v73
	s_nop 1
	v_mfma_f32_16x16x16_bf16 v[70:73], v[122:123], v[70:71], 0
	v_mfma_f32_16x16x16_bf16 v[180:183], v[120:121], v[102:103], v[180:183]
	s_nop 6
	v_cvt_pk_bf16_f32 v88, v70, v71
	v_cvt_pk_bf16_f32 v89, v72, v73
	s_nop 1
	v_mfma_f32_16x16x16_bf16 v[180:183], v[114:115], v[88:89], v[180:183]
	s_waitcnt lgkmcnt(4)
	v_mfma_f32_16x16x16_bf16 v[56:59], v[132:133], v[88:89], v[56:59]
	v_mfma_f32_16x16x16_bf16 v[64:67], v[136:137], v[88:89], v[64:67]
	v_mfma_f32_16x16x16_bf16 v[60:63], v[140:141], v[88:89], v[60:63]
	v_mfma_f32_16x16x16_bf16 v[52:55], v[144:145], v[88:89], v[52:55]
	v_mfma_f32_16x16x16_bf16 v[56:59], v[134:135], v[102:103], v[56:59]
	v_mfma_f32_16x16x16_bf16 v[64:67], v[138:139], v[102:103], v[64:67]
	v_mfma_f32_16x16x16_bf16 v[60:63], v[142:143], v[102:103], v[60:63]
	v_mfma_f32_16x16x16_bf16 v[52:55], v[146:147], v[102:103], v[52:55]
	s_waitcnt lgkmcnt(0)
	v_mov_b32_e32 v0, s50
	v_mov_b32_e32 v184, s7
	ds_write_b32 v0, v184
	v_cvt_pk_bf16_f32 v70, v180, v181
	v_cvt_pk_bf16_f32 v71, v182, v183
	s_nop 1
	v_mfma_f32_16x16x16_bf16 v[70:73], v[70:71], v[150:151], 0
	v_pk_mul_f32 v[56:57], v[124:125], v[56:57]
	v_pk_mul_f32 v[58:59], v[126:127], v[58:59]
	v_pk_mul_f32 v[64:65], v[160:161], v[64:65]
	v_pk_mul_f32 v[66:67], v[162:163], v[66:67]
	v_pk_mul_f32 v[60:61], v[168:169], v[60:61]
	v_pk_mul_f32 v[62:63], v[170:171], v[62:63]
	v_pk_mul_f32 v[52:53], v[176:177], v[52:53]
	v_pk_mul_f32 v[54:55], v[178:179], v[54:55]
	v_lshl_add_u64 v[166:167], v[2:3], 0, s[72:73]
	v_lshlrev_b64 v[166:167], 7, v[166:167]
	v_lshl_add_u64 v[166:167], v[68:69], 0, v[166:167]
	v_cvt_pk_bf16_f32 v70, v70, v71
	v_cvt_pk_bf16_f32 v71, v72, v73
	global_store_dwordx2 v[166:167], v[70:71], off
	s_cbranch_scc1 .LBB0_789

; #define LAS __attribute__((address_space(3)))
; __device__ void phase_rwkv_post(const Params& p, bf16_t* ymix, LAS unsigned char* lds, int wg, int nwg) {
;     ...
;         __syncthreads();
;         for (int i = tid; i < 4 * 64 * 32; i += 512) { const int ch = i >> 5, c16 = i & 31; *(LAS u32x4*)(lds + (ch * 264 + c16 * 8) * 2) = *(const u32x4*)(G2 + (size_t)(hg * 256 + ch) * 256 + c16 * 8); }
;         __syncthreads();
.LBB0_888:
	v_ashrrev_i32_e32 v7, 5, v1
	v_add_u32_e32 v2, s29, v7
	v_and_b32_e32 v6, 0xf8, v0
	v_lshlrev_b32_e32 v2, 9, v2
	v_lshl_add_u32 v2, v6, 1, v2
	s_mov_b64 s[98:99], s[4:5]
	global_load_dwordx4 v[100:103], v2, s[98:99]
	s_add_u32 s98, s98, 0x2000
	s_addc_u32 s99, s99, 0
	global_load_dwordx4 v[104:107], v2, s[98:99]
	s_add_u32 s98, s98, 0x2000
	s_addc_u32 s99, s99, 0
	global_load_dwordx4 v[108:111], v2, s[98:99]
	s_add_u32 s98, s98, 0x2000
	s_addc_u32 s99, s99, 0
	global_load_dwordx4 v[112:115], v2, s[98:99]
	s_add_u32 s98, s98, 0x2000
	s_addc_u32 s99, s99, 0
	global_load_dwordx4 v[116:119], v2, s[98:99]
	s_add_u32 s98, s98, 0x2000
	s_addc_u32 s99, s99, 0
	global_load_dwordx4 v[120:123], v2, s[98:99]
	s_add_u32 s98, s98, 0x2000
	s_addc_u32 s99, s99, 0
	global_load_dwordx4 v[124:127], v2, s[98:99]
	s_add_u32 s98, s98, 0x2000
	s_addc_u32 s99, s99, 0
	global_load_dwordx4 v[128:131], v2, s[98:99]
	s_add_u32 s98, s98, 0x2000
	s_addc_u32 s99, s99, 0
	global_load_dwordx4 v[132:135], v2, s[98:99]
	s_add_u32 s98, s98, 0x2000
	s_addc_u32 s99, s99, 0
	global_load_dwordx4 v[136:139], v2, s[98:99]
	s_add_u32 s98, s98, 0x2000
	s_addc_u32 s99, s99, 0
	global_load_dwordx4 v[140:143], v2, s[98:99]
	s_add_u32 s98, s98, 0x2000
	s_addc_u32 s99, s99, 0
	global_load_dwordx4 v[144:147], v2, s[98:99]
	s_add_u32 s98, s98, 0x2000
	s_addc_u32 s99, s99, 0
	global_load_dwordx4 v[148:151], v2, s[98:99]
	s_add_u32 s98, s98, 0x2000
	s_addc_u32 s99, s99, 0
	global_load_dwordx4 v[152:155], v2, s[98:99]
	s_add_u32 s98, s98, 0x2000
	s_addc_u32 s99, s99, 0
	global_load_dwordx4 v[156:159], v2, s[98:99]
	s_add_u32 s98, s98, 0x2000
	s_addc_u32 s99, s99, 0
	global_load_dwordx4 v[160:163], v2, s[98:99]
	v_mad_u32_u24 v6, v7, s33, v6
	v_lshl_add_u32 v6, v6, 1, 0
	v_add_u32_e32 v8, 0x10800, v6
	s_waitcnt vmcnt(15)
	ds_write_b128 v6, v[100:103]
	s_waitcnt vmcnt(14)
	ds_write_b128 v6, v[104:107] offset:8448
	s_waitcnt vmcnt(13)
	ds_write_b128 v6, v[108:111] offset:16896
	s_waitcnt vmcnt(12)
	ds_write_b128 v6, v[112:115] offset:25344
	s_waitcnt vmcnt(11)
	ds_write_b128 v6, v[116:119] offset:33792
	s_waitcnt vmcnt(10)
	ds_write_b128 v6, v[120:123] offset:42240
	s_waitcnt vmcnt(9)
	ds_write_b128 v6, v[124:127] offset:50688
	s_waitcnt vmcnt(8)
	ds_write_b128 v6, v[128:131] offset:59136
	s_waitcnt vmcnt(7)
	ds_write_b128 v8, v[132:135]
	s_waitcnt vmcnt(6)
	ds_write_b128 v8, v[136:139] offset:8448
	s_waitcnt vmcnt(5)
	ds_write_b128 v8, v[140:143] offset:16896
	s_waitcnt vmcnt(4)
	ds_write_b128 v8, v[144:147] offset:25344
	s_waitcnt vmcnt(3)
	ds_write_b128 v8, v[148:151] offset:33792
	s_waitcnt vmcnt(2)
	ds_write_b128 v8, v[152:155] offset:42240
	s_waitcnt vmcnt(1)
	ds_write_b128 v8, v[156:159] offset:50688
	s_waitcnt vmcnt(0)
	ds_write_b128 v8, v[160:163] offset:59136
	s_or_b64 exec, exec, s[26:27]
	v_mov_b32_e32 v0, s29
